# stack19 + SwiGLU epilogue first half (4 store groups, accumulators v66-129) executed inside the last MFMA phase of the K-loop's last iteration (F1a, F2a)
# baseline (speedup 1.0000x reference)
; #define PG8_STAGE(bufoff, gbase, voff) do { _Pragma("unroll") for (int _i = 0; _i < 2; ++_i) \
;         __builtin_amdgcn_global_load_lds((const unsigned*)((const char*)(gbase) + (voff)[_i]), (PG8_LAS unsigned*)(lds + (bufoff) + ldsw + _i * 8192), 16, 0, 0); } while (0)
; #define PG8_LDA(dst, b, h) do { _Pragma("unroll") for (int m = 0; m < 4; ++m) _Pragma("unroll") for (int k = 0; k < 2; ++k) dst[m][k] = *(const PG8_LAS bf16x8*)(lds + PG8_SA(b, h) + aoff + m * 2048 + k * 1024); } while (0)
; #define PG8_LDB(dst, b, h) do { _Pragma("unroll") for (int n = 0; n < 2; ++n) _Pragma("unroll") for (int k = 0; k < 2; ++k) dst[n][k] = *(const PG8_LAS bf16x8*)(lds + PG8_SB(b, h) + boff + n * 2048 + k * 1024); } while (0)
; #define PG8_MMA(ai, bj, At, Bt) do { __builtin_amdgcn_s_setprio(1); _Pragma("unroll") for (int m = 0; m < 4; ++m) _Pragma("unroll") for (int n = 0; n < 2; ++n) _Pragma("unroll") for (int k = 0; k < 2; ++k) \
;         acc[ai][bj][m][n] = __builtin_amdgcn_mfma_f32_16x16x32_bf16(Bt[n][k], At[m][k], acc[ai][bj][m][n], 0, 0, 0); __builtin_amdgcn_s_setprio(0); } while (0)
; #define PG8_WAIT_V(n) asm volatile("s_waitcnt vmcnt(" #n ")" ::: "memory")
; #define PG8_WAIT_L(n) asm volatile("s_waitcnt lgkmcnt(" #n ")" ::: "memory")
; #define PG8_BAR __builtin_amdgcn_s_barrier()
; #define PG8_SCHED __builtin_amdgcn_sched_barrier(0)
; template <class Epi, class Sched, bool ALIGN_EPI = false, bool SP2 = false, bool ABLK = false, bool BBLK = false>
; __device__ __forceinline__ void gemm_phase(PG8_LAS unsigned char* lds, const Gemm g, const Sched& S, const Epi& E) {
;     ...
;             PG8_LDB(B0, 1, 0); PG8_LDB(B1, 1, 1); PG8_SCHED; PG8_LDA(At, 1, 0); PG8_STAGE(PG8_SA(0, 1), a2 + hstepA, voffA);
;             PG8_WAIT_V(8); PG8_WAIT_L(0); PG8_BAR; PG8_MMA(0, 0, At, B0); PG8_MMA(0, 1, At, B1); PG8_BAR; PG8_SCHED;
;             PG8_LDA(At, 1, 1); PG8_STAGE(PG8_SB(1, 0), b3, voffB); PG8_STAGE(PG8_SB(1, 1), b3 + hstepB, voffB); PG8_STAGE(PG8_SA(1, 0), a3, voffA);
.Lmid_216:
	s_add_i32 s75, 0, 0x18000
	v_add_u32_e32 v142, s75, v145
	s_add_i32 s80, 0, 0x1c000
	ds_read_b128 v[148:151], v142
	ds_read_b128 v[152:155], v142 offset:1024
	ds_read_b128 v[156:159], v142 offset:2048
	ds_read_b128 v[160:163], v142 offset:3072
	v_add_u32_e32 v142, s80, v145
	ds_read_b128 v[164:167], v142
	ds_read_b128 v[168:171], v142 offset:1024
	ds_read_b128 v[172:175], v142 offset:2048
	ds_read_b128 v[176:179], v142 offset:3072
	s_add_u32 s28, s28, 0x4000
	s_addc_u32 s29, s29, 0
	s_mov_b32 m0, s45
	v_lshl_add_u64 v[142:143], s[28:29], 0, v[136:137]
	ds_read_b128 v[180:183], v146 offset:32768
	ds_read_b128 v[196:199], v146 offset:33792
	ds_read_b128 v[200:203], v146 offset:34816
	ds_read_b128 v[204:207], v146 offset:35840
	ds_read_b128 v[208:211], v146 offset:36864
	ds_read_b128 v[212:215], v146 offset:37888
	ds_read_b128 v[216:219], v146 offset:38912
	ds_read_b128 v[220:223], v146 offset:39936
	global_load_lds_dwordx4 v[142:143], off
	v_lshl_add_u64 v[142:143], s[28:29], 0, v[132:133]
	s_mov_b32 m0, s46
	s_nop 0
	global_load_lds_dwordx4 v[142:143], off
	s_waitcnt vmcnt(8)
	s_waitcnt lgkmcnt(0)
	s_barrier
	s_setprio 1
	s_waitcnt lgkmcnt(0)
	v_mfma_f32_16x16x32_bf16 v[126:129], v[148:151], v[180:183], v[126:129]
	v_mfma_f32_16x16x32_bf16 v[118:121], v[156:159], v[180:183], v[118:121]
	v_mfma_f32_16x16x32_bf16 v[110:113], v[148:151], v[200:203], v[110:113]
	v_mfma_f32_16x16x32_bf16 v[102:105], v[156:159], v[200:203], v[102:105]
	v_mfma_f32_16x16x32_bf16 v[94:97], v[148:151], v[208:211], v[94:97]
	v_mfma_f32_16x16x32_bf16 v[86:89], v[156:159], v[208:211], v[86:89]
	v_mfma_f32_16x16x32_bf16 v[78:81], v[148:151], v[216:219], v[78:81]
	v_mfma_f32_16x16x32_bf16 v[70:73], v[156:159], v[216:219], v[70:73]
	v_mfma_f32_16x16x32_bf16 v[126:129], v[152:155], v[196:199], v[126:129]
	v_mfma_f32_16x16x32_bf16 v[118:121], v[160:163], v[196:199], v[118:121]
	v_mfma_f32_16x16x32_bf16 v[110:113], v[152:155], v[204:207], v[110:113]
	v_mfma_f32_16x16x32_bf16 v[102:105], v[160:163], v[204:207], v[102:105]
	v_mfma_f32_16x16x32_bf16 v[94:97], v[152:155], v[212:215], v[94:97]
	v_mfma_f32_16x16x32_bf16 v[86:89], v[160:163], v[212:215], v[86:89]
	v_mfma_f32_16x16x32_bf16 v[78:81], v[152:155], v[220:223], v[78:81]
	v_mfma_f32_16x16x32_bf16 v[70:73], v[160:163], v[220:223], v[70:73]
	s_setprio 0
	s_setprio 1
	v_mfma_f32_16x16x32_bf16 v[122:125], v[164:167], v[180:183], v[122:125]
	v_mfma_f32_16x16x32_bf16 v[114:117], v[172:175], v[180:183], v[114:117]
	v_mfma_f32_16x16x32_bf16 v[106:109], v[164:167], v[200:203], v[106:109]
	v_mfma_f32_16x16x32_bf16 v[98:101], v[172:175], v[200:203], v[98:101]
	v_mfma_f32_16x16x32_bf16 v[90:93], v[164:167], v[208:211], v[90:93]
	v_mfma_f32_16x16x32_bf16 v[82:85], v[172:175], v[208:211], v[82:85]
	v_mfma_f32_16x16x32_bf16 v[74:77], v[164:167], v[216:219], v[74:77]
	v_mfma_f32_16x16x32_bf16 v[66:69], v[172:175], v[216:219], v[66:69]
	v_mfma_f32_16x16x32_bf16 v[122:125], v[168:171], v[196:199], v[122:125]
	v_mfma_f32_16x16x32_bf16 v[114:117], v[176:179], v[196:199], v[114:117]
	v_mfma_f32_16x16x32_bf16 v[106:109], v[168:171], v[204:207], v[106:109]
	v_mfma_f32_16x16x32_bf16 v[98:101], v[176:179], v[204:207], v[98:101]
	v_mfma_f32_16x16x32_bf16 v[90:93], v[168:171], v[212:215], v[90:93]
	v_mfma_f32_16x16x32_bf16 v[82:85], v[176:179], v[212:215], v[82:85]
	v_mfma_f32_16x16x32_bf16 v[74:77], v[168:171], v[220:223], v[74:77]
	v_mfma_f32_16x16x32_bf16 v[66:69], v[176:179], v[220:223], v[66:69]
	s_setprio 0
	s_barrier
	s_add_u32 s28, s26, 0x8000
	s_addc_u32 s29, s27, 0
	s_add_i32 s75, s75, s41
	v_lshl_add_u64 v[142:143], s[28:29], 0, v[134:135]
	s_mov_b32 m0, s75
	ds_read_b128 v[180:183], v146 offset:49152
	ds_read_b128 v[196:199], v146 offset:50176
	ds_read_b128 v[200:203], v146 offset:51200
	ds_read_b128 v[204:207], v146 offset:52224
	ds_read_b128 v[208:211], v146 offset:53248
	ds_read_b128 v[212:215], v146 offset:54272
	ds_read_b128 v[216:219], v146 offset:55296
	ds_read_b128 v[220:223], v146 offset:56320
	global_load_lds_dwordx4 v[142:143], off
	s_add_i32 m0, s75, 0x2000
	s_add_u32 s26, s26, 0xc000
	v_lshl_add_u64 v[142:143], s[28:29], 0, v[130:131]
	s_addc_u32 s27, s27, 0
	s_add_i32 s28, s80, s41
	global_load_lds_dwordx4 v[142:143], off
	v_lshl_add_u64 v[142:143], s[26:27], 0, v[134:135]
	s_mov_b32 m0, s28
	s_nop 0
	global_load_lds_dwordx4 v[142:143], off
	v_lshl_add_u64 v[142:143], s[26:27], 0, v[130:131]
	s_add_i32 m0, s28, 0x2000
	s_nop 0
	global_load_lds_dwordx4 v[142:143], off
	v_lshl_add_u64 v[142:143], s[24:25], 0, v[136:137]
	s_mov_b32 m0, s51
	s_nop 0
	global_load_lds_dwordx4 v[142:143], off
	v_lshl_add_u64 v[142:143], s[24:25], 0, v[132:133]
	s_mov_b32 m0, s53
	s_nop 0
	global_load_lds_dwordx4 v[142:143], off
	s_cmp_eq_u32 s81, 28
	s_cbranch_scc1 .Llast_216
	s_waitcnt vmcnt(8)
	s_waitcnt lgkmcnt(0)
	s_barrier
; __device__ __forceinline__ float fast_sigmoid(float x) { return __builtin_amdgcn_rcpf(1.0f + __builtin_amdgcn_exp2f(-1.4426950408889634f * x)); }
; __device__ __forceinline__ u32x4 pack8(const f32x4 v0, const f32x4 v1) { u32x4 w; w.x = cvt_pk_bf16(v0[0], v0[1]); w.y = cvt_pk_bf16(v0[2], v0[3]); w.z = cvt_pk_bf16(v1[0], v1[1]); w.w = cvt_pk_bf16(v1[2], v1[3]); return w; }
; #define PG8_STAGE(bufoff, gbase, voff) do { _Pragma("unroll") for (int _i = 0; _i < 2; ++_i) \
;         __builtin_amdgcn_global_load_lds((const unsigned*)((const char*)(gbase) + (voff)[_i]), (PG8_LAS unsigned*)(lds + (bufoff) + ldsw + _i * 8192), 16, 0, 0); } while (0)
; #define PG8_LDA(dst, b, h) do { _Pragma("unroll") for (int m = 0; m < 4; ++m) _Pragma("unroll") for (int k = 0; k < 2; ++k) dst[m][k] = *(const PG8_LAS bf16x8*)(lds + PG8_SA(b, h) + aoff + m * 2048 + k * 1024); } while (0)
; #define PG8_WAIT_V(n) asm volatile("s_waitcnt vmcnt(" #n ")" ::: "memory")
; #define PG8_WAIT_L(n) asm volatile("s_waitcnt lgkmcnt(" #n ")" ::: "memory")
; #define PG8_BAR __builtin_amdgcn_s_barrier()
;     __device__ __forceinline__ void operator()(const f32x4 (&acc)[2][2][4][2], const Unit& u, int wr, int wc, int fr_, int fq) const {
;     ...
;         bf16_t* Hblk = H + ((size_t)(u.pm * (ldh / BK) + 2 * u.pn + (wc >> 1)) * BM + wr * 64 + fr) * BK + (wc & 1) * 32 + 8 * fq;
; #pragma unroll
;         for (int ai = 0; ai < 2; ++ai)
; #pragma unroll
;             for (int m = 0; m < 4; ++m) {
;                 f32x4 v0, v1;
; #pragma unroll
;                 for (int j = 0; j < 4; ++j) { const float g0 = acc[ai][0][m][0][j], g1 = acc[ai][0][m][1][j];
;                     v0[j] = g0 * fast_sigmoid(g0) * acc[ai][1][m][0][j]; v1[j] = g1 * fast_sigmoid(g1) * acc[ai][1][m][1][j]; }
;                 *(u32x4*)(Hblk + (size_t)(ai * HALF + m * 16) * BK) = pack8(v0, v1); }
; template <class Epi, class Sched, bool ALIGN_EPI = false, bool SP2 = false, bool ABLK = false, bool BBLK = false>
; __device__ __forceinline__ void gemm_phase(PG8_LAS unsigned char* lds, const Gemm g, const Sched& S, const Epi& E) {
;     ...
;             PG8_LDA(At, 1, 1); PG8_STAGE(PG8_SB(1, 0), b3, voffB); PG8_STAGE(PG8_SB(1, 1), b3 + hstepB, voffB); PG8_STAGE(PG8_SA(1, 0), a3, voffA);
;             PG8_WAIT_V(8); PG8_WAIT_L(0); PG8_BAR; PG8_MMA(1, 0, At, B0); PG8_MMA(1, 1, At, B1); PG8_BAR; PG8_SCHED;
	s_setprio 1
	s_waitcnt lgkmcnt(0)
	v_mfma_f32_16x16x32_bf16 v[62:65], v[148:151], v[180:183], v[62:65]
	v_mfma_f32_16x16x32_bf16 v[54:57], v[156:159], v[180:183], v[54:57]
	v_mfma_f32_16x16x32_bf16 v[46:49], v[148:151], v[200:203], v[46:49]
	v_mfma_f32_16x16x32_bf16 v[38:41], v[156:159], v[200:203], v[38:41]
	v_mfma_f32_16x16x32_bf16 v[30:33], v[148:151], v[208:211], v[30:33]
	v_mfma_f32_16x16x32_bf16 v[22:25], v[156:159], v[208:211], v[22:25]
	v_mfma_f32_16x16x32_bf16 v[14:17], v[148:151], v[216:219], v[14:17]
	v_mfma_f32_16x16x32_bf16 v[6:9], v[156:159], v[216:219], v[6:9]
	v_mfma_f32_16x16x32_bf16 v[62:65], v[152:155], v[196:199], v[62:65]
	v_mfma_f32_16x16x32_bf16 v[54:57], v[160:163], v[196:199], v[54:57]
	v_mfma_f32_16x16x32_bf16 v[46:49], v[152:155], v[204:207], v[46:49]
	v_mfma_f32_16x16x32_bf16 v[38:41], v[160:163], v[204:207], v[38:41]
	v_mfma_f32_16x16x32_bf16 v[30:33], v[152:155], v[212:215], v[30:33]
	v_mfma_f32_16x16x32_bf16 v[22:25], v[160:163], v[212:215], v[22:25]
	v_mfma_f32_16x16x32_bf16 v[14:17], v[152:155], v[220:223], v[14:17]
	v_mfma_f32_16x16x32_bf16 v[6:9], v[160:163], v[220:223], v[6:9]
	s_setprio 0
	s_setprio 1
	v_mfma_f32_16x16x32_bf16 v[58:61], v[164:167], v[180:183], v[58:61]
	v_mfma_f32_16x16x32_bf16 v[50:53], v[172:175], v[180:183], v[50:53]
	v_mfma_f32_16x16x32_bf16 v[42:45], v[164:167], v[200:203], v[42:45]
	v_mfma_f32_16x16x32_bf16 v[34:37], v[172:175], v[200:203], v[34:37]
	v_mfma_f32_16x16x32_bf16 v[26:29], v[164:167], v[208:211], v[26:29]
	v_mfma_f32_16x16x32_bf16 v[18:21], v[172:175], v[208:211], v[18:21]
	v_mfma_f32_16x16x32_bf16 v[10:13], v[164:167], v[216:219], v[10:13]
	v_mfma_f32_16x16x32_bf16 v[2:5], v[172:175], v[216:219], v[2:5]
	v_mfma_f32_16x16x32_bf16 v[58:61], v[168:171], v[196:199], v[58:61]
	v_mfma_f32_16x16x32_bf16 v[50:53], v[176:179], v[196:199], v[50:53]
	v_mfma_f32_16x16x32_bf16 v[42:45], v[168:171], v[204:207], v[42:45]
	v_mfma_f32_16x16x32_bf16 v[34:37], v[176:179], v[204:207], v[34:37]
	v_mfma_f32_16x16x32_bf16 v[26:29], v[168:171], v[212:215], v[26:29]
	v_mfma_f32_16x16x32_bf16 v[18:21], v[176:179], v[212:215], v[18:21]
	v_mfma_f32_16x16x32_bf16 v[10:13], v[168:171], v[220:223], v[10:13]
	v_mfma_f32_16x16x32_bf16 v[2:5], v[176:179], v[220:223], v[2:5]
	s_setprio 0
	s_barrier
	s_add_i32 s81, s81, 2
	s_add_u32 s22, s22, 0x10000
	s_addc_u32 s23, s23, 0
	s_add_u32 s72, s72, 0x10000
	s_addc_u32 s73, s73, 0
	s_cmp_gt_u32 s81, 29
	s_cbranch_scc0 .LBB0_216
	s_branch .Lpost_216
.Llast_216:
	s_waitcnt vmcnt(8)
	s_waitcnt lgkmcnt(0)
	s_barrier
	s_setprio 1
	s_waitcnt lgkmcnt(0)
	v_mfma_f32_16x16x32_bf16 v[62:65], v[148:151], v[180:183], v[62:65]
	v_mov_b32_e32 v184, 0xbfb8aa3b
	v_mov_b32_e32 v185, 0xbfb8aa3b
	v_mov_b32_e32 v188, 1.0
	v_mov_b32_e32 v189, 1.0
	v_pk_mul_f32 v[190:191], v[126:127], v[184:185]
	v_pk_mul_f32 v[192:193], v[128:129], v[184:185]
	v_mfma_f32_16x16x32_bf16 v[54:57], v[156:159], v[180:183], v[54:57]
	v_pk_mul_f32 v[224:225], v[118:119], v[184:185]
	v_pk_mul_f32 v[226:227], v[120:121], v[184:185]
	v_exp_f32_e32 v190, v190
	v_exp_f32_e32 v191, v191
	v_exp_f32_e32 v192, v192
	v_exp_f32_e32 v193, v193
	v_mfma_f32_16x16x32_bf16 v[46:49], v[148:151], v[200:203], v[46:49]
	v_exp_f32_e32 v224, v224
	v_exp_f32_e32 v225, v225
	v_exp_f32_e32 v226, v226
	v_exp_f32_e32 v227, v227
	v_pk_add_f32 v[190:191], v[190:191], v[188:189]
	v_pk_add_f32 v[192:193], v[192:193], v[188:189]
	v_mfma_f32_16x16x32_bf16 v[38:41], v[156:159], v[200:203], v[38:41]
	v_pk_add_f32 v[224:225], v[224:225], v[188:189]
	v_pk_add_f32 v[226:227], v[226:227], v[188:189]
	v_rcp_f32_e32 v190, v190
	v_rcp_f32_e32 v191, v191
	v_rcp_f32_e32 v192, v192
	v_rcp_f32_e32 v193, v193
	v_mfma_f32_16x16x32_bf16 v[30:33], v[148:151], v[208:211], v[30:33]
	v_rcp_f32_e32 v224, v224
	v_rcp_f32_e32 v225, v225
	v_rcp_f32_e32 v226, v226
	v_rcp_f32_e32 v227, v227
	v_pk_mul_f32 v[126:127], v[126:127], v[190:191]
	v_pk_mul_f32 v[128:129], v[128:129], v[192:193]
	v_mfma_f32_16x16x32_bf16 v[22:25], v[156:159], v[208:211], v[22:25]
	v_pk_mul_f32 v[118:119], v[118:119], v[224:225]
	v_pk_mul_f32 v[120:121], v[120:121], v[226:227]
	v_pk_mul_f32 v[126:127], v[126:127], v[122:123]
	v_pk_mul_f32 v[128:129], v[128:129], v[124:125]
	v_pk_mul_f32 v[118:119], v[118:119], v[114:115]
	v_pk_mul_f32 v[120:121], v[120:121], v[116:117]
	v_mfma_f32_16x16x32_bf16 v[14:17], v[148:151], v[216:219], v[14:17]
	v_cvt_pk_bf16_f32 v114, v126, v127
	v_cvt_pk_bf16_f32 v115, v128, v129
	v_cvt_pk_bf16_f32 v116, v118, v119
	v_cvt_pk_bf16_f32 v117, v120, v121
	s_lshl_b32 s1, s1, 1
	s_mulk_i32 s0, 0x58
	v_mfma_f32_16x16x32_bf16 v[6:9], v[156:159], v[216:219], v[6:9]
	s_or_b32 s1, s1, s56
	s_add_i32 s0, s1, s0
	v_mov_b32_e32 v142, v144
	s_ashr_i32 s1, s0, 31
	s_lshl_b64 s[0:1], s[0:1], 15
	v_ashrrev_i32_e32 v143, 31, v142
	v_mfma_f32_16x16x32_bf16 v[62:65], v[152:155], v[196:199], v[62:65]
	v_lshl_add_u64 v[142:143], v[142:143], 0, s[8:9]
	s_add_u32 s0, s47, s0
	v_lshlrev_b64 v[142:143], 7, v[142:143]
	s_addc_u32 s1, s50, s1
	v_lshl_add_u64 v[142:143], s[0:1], 0, v[142:143]
	v_lshl_add_u64 v[142:143], v[142:143], 0, s[16:17]
	v_mfma_f32_16x16x32_bf16 v[54:57], v[160:163], v[196:199], v[54:57]
	v_lshl_add_u64 v[142:143], v[142:143], 0, v[186:187]
	s_movk_i32 s0, 0x5000
	global_store_dwordx4 v[142:143], v[114:117], off
	v_pk_mul_f32 v[190:191], v[110:111], v[184:185]
	v_pk_mul_f32 v[192:193], v[112:113], v[184:185]
	v_pk_mul_f32 v[224:225], v[102:103], v[184:185]
	v_mfma_f32_16x16x32_bf16 v[46:49], v[152:155], v[204:207], v[46:49]
	v_pk_mul_f32 v[226:227], v[104:105], v[184:185]
	v_exp_f32_e32 v190, v190
	v_exp_f32_e32 v191, v191
	v_exp_f32_e32 v192, v192
; __device__ __forceinline__ float fast_sigmoid(float x) { return __builtin_amdgcn_rcpf(1.0f + __builtin_amdgcn_exp2f(-1.4426950408889634f * x)); }
; #define PG8_BAR __builtin_amdgcn_s_barrier()
;     __device__ __forceinline__ void operator()(const f32x4 (&acc)[2][2][4][2], const Unit& u, int wr, int wc, int fr_, int fq) const {
;     ...
;                 for (int j = 0; j < 4; ++j) { const float g0 = acc[ai][0][m][0][j], g1 = acc[ai][0][m][1][j];
;                     v0[j] = g0 * fast_sigmoid(g0) * acc[ai][1][m][0][j]; v1[j] = g1 * fast_sigmoid(g1) * acc[ai][1][m][1][j]; }
;                 *(u32x4*)(Hblk + (size_t)(ai * HALF + m * 16) * BK) = pack8(v0, v1); }
; template <class Epi, class Sched, bool ALIGN_EPI = false, bool SP2 = false, bool ABLK = false, bool BBLK = false>
; __device__ __forceinline__ void gemm_phase(PG8_LAS unsigned char* lds, const Gemm g, const Sched& S, const Epi& E) {
;     ...
;             PG8_WAIT_V(8); PG8_WAIT_L(0); PG8_BAR; PG8_MMA(1, 0, At, B0); PG8_MMA(1, 1, At, B1); PG8_BAR; PG8_SCHED;
;             } else {
;             PG8_LDB(B0, 0, 0); PG8_SCHED; PG8_LDA(At, 0, 0); PG8_STAGE(PG8_SA(1, 1), a1 + hstepA, voffA);
;             PG8_WAIT_L(8); PG8_BAR; PG8_WAIT_L(0); PG8_MMA(0, 0, At, B0); PG8_BAR; PG8_SCHED;
;             PG8_LDB(B1, 0, 1); PG8_STAGE(PG8_SB(0, 0), b2, voffB);
;             PG8_BAR; PG8_WAIT_L(0); PG8_MMA(0, 1, At, B1); PG8_BAR;
;             PG8_LDA(At, 0, 1); PG8_STAGE(PG8_SA(0, 0), a2, voffA);
;             PG8_BAR; PG8_WAIT_L(0); PG8_MMA(1, 0, At, B0); PG8_BAR; PG8_SCHED;
;             PG8_STAGE(PG8_SB(0, 1), b2 + hstepB, voffB);
;             PG8_WAIT_V(6); PG8_BAR; PG8_MMA(1, 1, At, B1); PG8_BAR;
;             PG8_LDB(B0, 1, 0); PG8_SCHED; PG8_LDA(At, 1, 0); PG8_STAGE(PG8_SA(0, 1), a2 + hstepA, voffA);
;             PG8_WAIT_L(8); PG8_BAR; PG8_WAIT_L(0); PG8_MMA(0, 0, At, B0); PG8_BAR; PG8_SCHED;
;             PG8_LDB(B1, 1, 1); PG8_STAGE(PG8_SB(1, 0), b3, voffB);
;             PG8_BAR; PG8_WAIT_L(0); PG8_MMA(0, 1, At, B1); PG8_BAR;
;             PG8_LDA(At, 1, 1); PG8_STAGE(PG8_SA(1, 0), a3, voffA);
;             PG8_BAR; PG8_WAIT_L(0); PG8_MMA(1, 0, At, B0); PG8_BAR; PG8_SCHED;
;             PG8_STAGE(PG8_SB(1, 1), b3 + hstepB, voffB);
;             PG8_WAIT_V(6); PG8_BAR; PG8_MMA(1, 1, At, B1); PG8_BAR;
;             }
;         }
;         if constexpr (ALIGN_EPI) { if (wr == 0) PG8_BAR; }
	v_exp_f32_e32 v193, v193
	v_exp_f32_e32 v224, v224
	v_mfma_f32_16x16x32_bf16 v[38:41], v[160:163], v[204:207], v[38:41]
	v_exp_f32_e32 v225, v225
	v_exp_f32_e32 v226, v226
	v_exp_f32_e32 v227, v227
	v_pk_add_f32 v[190:191], v[190:191], v[188:189]
	v_pk_add_f32 v[192:193], v[192:193], v[188:189]
	v_pk_add_f32 v[224:225], v[224:225], v[188:189]
	v_mfma_f32_16x16x32_bf16 v[30:33], v[152:155], v[212:215], v[30:33]
	v_pk_add_f32 v[226:227], v[226:227], v[188:189]
	v_rcp_f32_e32 v190, v190
	v_rcp_f32_e32 v191, v191
	v_rcp_f32_e32 v192, v192
	v_rcp_f32_e32 v193, v193
	v_rcp_f32_e32 v224, v224
	v_mfma_f32_16x16x32_bf16 v[22:25], v[160:163], v[212:215], v[22:25]
	v_rcp_f32_e32 v225, v225
	v_rcp_f32_e32 v226, v226
	v_rcp_f32_e32 v227, v227
	v_pk_mul_f32 v[110:111], v[110:111], v[190:191]
	v_pk_mul_f32 v[112:113], v[112:113], v[192:193]
	v_pk_mul_f32 v[102:103], v[102:103], v[224:225]
	v_mfma_f32_16x16x32_bf16 v[14:17], v[152:155], v[220:223], v[14:17]
	v_pk_mul_f32 v[104:105], v[104:105], v[226:227]
	v_pk_mul_f32 v[110:111], v[110:111], v[106:107]
	v_pk_mul_f32 v[112:113], v[112:113], v[108:109]
	v_pk_mul_f32 v[102:103], v[102:103], v[98:99]
	v_pk_mul_f32 v[104:105], v[104:105], v[100:101]
	v_cvt_pk_bf16_f32 v98, v110, v111
	v_mfma_f32_16x16x32_bf16 v[6:9], v[160:163], v[220:223], v[6:9]
	v_cvt_pk_bf16_f32 v99, v112, v113
	v_cvt_pk_bf16_f32 v100, v102, v103
	v_cvt_pk_bf16_f32 v101, v104, v105
	global_store_dwordx4 v[142:143], v[98:101], off offset:2048
	v_pk_mul_f32 v[190:191], v[94:95], v[184:185]
	v_pk_mul_f32 v[192:193], v[96:97], v[184:185]
	s_setprio 0
	s_setprio 1
	v_mfma_f32_16x16x32_bf16 v[58:61], v[164:167], v[180:183], v[58:61]
	v_pk_mul_f32 v[224:225], v[86:87], v[184:185]
	v_pk_mul_f32 v[226:227], v[88:89], v[184:185]
	v_exp_f32_e32 v190, v190
	v_exp_f32_e32 v191, v191
	v_exp_f32_e32 v192, v192
	v_exp_f32_e32 v193, v193
	v_mfma_f32_16x16x32_bf16 v[50:53], v[172:175], v[180:183], v[50:53]
	v_exp_f32_e32 v224, v224
	v_exp_f32_e32 v225, v225
	v_exp_f32_e32 v226, v226
	v_exp_f32_e32 v227, v227
	v_pk_add_f32 v[190:191], v[190:191], v[188:189]
	v_pk_add_f32 v[192:193], v[192:193], v[188:189]
	v_mfma_f32_16x16x32_bf16 v[42:45], v[164:167], v[200:203], v[42:45]
	v_pk_add_f32 v[224:225], v[224:225], v[188:189]
	v_pk_add_f32 v[226:227], v[226:227], v[188:189]
	v_rcp_f32_e32 v190, v190
	v_rcp_f32_e32 v191, v191
	v_rcp_f32_e32 v192, v192
	v_rcp_f32_e32 v193, v193
	v_mfma_f32_16x16x32_bf16 v[34:37], v[172:175], v[200:203], v[34:37]
	v_rcp_f32_e32 v224, v224
	v_rcp_f32_e32 v225, v225
	v_rcp_f32_e32 v226, v226
	v_rcp_f32_e32 v227, v227
	v_pk_mul_f32 v[94:95], v[94:95], v[190:191]
	v_pk_mul_f32 v[96:97], v[96:97], v[192:193]
	v_mfma_f32_16x16x32_bf16 v[26:29], v[164:167], v[208:211], v[26:29]
	v_pk_mul_f32 v[86:87], v[86:87], v[224:225]
	v_pk_mul_f32 v[88:89], v[88:89], v[226:227]
	v_pk_mul_f32 v[94:95], v[94:95], v[90:91]
	v_pk_mul_f32 v[96:97], v[96:97], v[92:93]
	v_pk_mul_f32 v[86:87], v[86:87], v[82:83]
	v_pk_mul_f32 v[88:89], v[88:89], v[84:85]
	v_mfma_f32_16x16x32_bf16 v[18:21], v[172:175], v[208:211], v[18:21]
	v_cvt_pk_bf16_f32 v82, v94, v95
	v_cvt_pk_bf16_f32 v83, v96, v97
	v_cvt_pk_bf16_f32 v84, v86, v87
	v_cvt_pk_bf16_f32 v85, v88, v89
	v_add_co_u32_e32 v86, vcc, s67, v142
	s_nop 1
	v_mfma_f32_16x16x32_bf16 v[10:13], v[164:167], v[216:219], v[10:13]
	v_addc_co_u32_e32 v87, vcc, 0, v143, vcc
	global_store_dwordx4 v[86:87], v[82:85], off
	v_pk_mul_f32 v[190:191], v[78:79], v[184:185]
	v_pk_mul_f32 v[192:193], v[80:81], v[184:185]
	v_pk_mul_f32 v[224:225], v[70:71], v[184:185]
	v_pk_mul_f32 v[226:227], v[72:73], v[184:185]
	v_mfma_f32_16x16x32_bf16 v[2:5], v[172:175], v[216:219], v[2:5]
	v_exp_f32_e32 v190, v190
	v_exp_f32_e32 v191, v191
	v_exp_f32_e32 v192, v192
	v_exp_f32_e32 v193, v193
	v_exp_f32_e32 v224, v224
	v_exp_f32_e32 v225, v225
	v_mfma_f32_16x16x32_bf16 v[58:61], v[168:171], v[196:199], v[58:61]
	v_exp_f32_e32 v226, v226
	v_exp_f32_e32 v227, v227
	v_pk_add_f32 v[190:191], v[190:191], v[188:189]
	v_pk_add_f32 v[192:193], v[192:193], v[188:189]
	v_pk_add_f32 v[224:225], v[224:225], v[188:189]
	v_pk_add_f32 v[226:227], v[226:227], v[188:189]
	v_mfma_f32_16x16x32_bf16 v[50:53], v[176:179], v[196:199], v[50:53]
	v_rcp_f32_e32 v190, v190
	v_rcp_f32_e32 v191, v191
	v_rcp_f32_e32 v192, v192
	v_rcp_f32_e32 v193, v193
	v_rcp_f32_e32 v224, v224
	v_rcp_f32_e32 v225, v225
	v_mfma_f32_16x16x32_bf16 v[42:45], v[168:171], v[204:207], v[42:45]
	v_rcp_f32_e32 v226, v226
	v_rcp_f32_e32 v227, v227
	v_pk_mul_f32 v[78:79], v[78:79], v[190:191]
	v_pk_mul_f32 v[80:81], v[80:81], v[192:193]
	v_pk_mul_f32 v[70:71], v[70:71], v[224:225]
	v_pk_mul_f32 v[72:73], v[72:73], v[226:227]
	v_mfma_f32_16x16x32_bf16 v[34:37], v[176:179], v[204:207], v[34:37]
	v_pk_mul_f32 v[78:79], v[78:79], v[74:75]
	v_pk_mul_f32 v[80:81], v[80:81], v[76:77]
	v_pk_mul_f32 v[70:71], v[70:71], v[66:67]
	v_pk_mul_f32 v[72:73], v[72:73], v[68:69]
	v_cvt_pk_bf16_f32 v66, v78, v79
	v_cvt_pk_bf16_f32 v67, v80, v81
	v_mfma_f32_16x16x32_bf16 v[26:29], v[168:171], v[212:215], v[26:29]
	v_cvt_pk_bf16_f32 v68, v70, v71
	v_cvt_pk_bf16_f32 v69, v72, v73
	global_store_dwordx4 v[86:87], v[66:69], off offset:2048
	v_mfma_f32_16x16x32_bf16 v[18:21], v[176:179], v[212:215], v[18:21]
	v_mfma_f32_16x16x32_bf16 v[10:13], v[168:171], v[220:223], v[10:13]
	v_mfma_f32_16x16x32_bf16 v[2:5], v[176:179], v[220:223], v[2:5]
	s_setprio 0
	s_barrier
	s_add_i32 s81, s81, 2
	s_add_u32 s22, s22, 0x10000
	s_addc_u32 s23, s23, 0
	s_add_u32 s72, s72, 0x10000
	s_addc_u32 s73, s73, 0
	s_branch .Lpost_216
.Lpost_216:
	s_and_b64 vcc, exec, s[10:11]
	s_cbranch_vccz .LBB0_219
	s_barrier
; __device__ __forceinline__ float fast_sigmoid(float x) { return __builtin_amdgcn_rcpf(1.0f + __builtin_amdgcn_exp2f(-1.4426950408889634f * x)); }
; __device__ __forceinline__ u32x4 pack8(const f32x4 v0, const f32x4 v1) { u32x4 w; w.x = cvt_pk_bf16(v0[0], v0[1]); w.y = cvt_pk_bf16(v0[2], v0[3]); w.z = cvt_pk_bf16(v1[0], v1[1]); w.w = cvt_pk_bf16(v1[2], v1[3]); return w; }
; #define PG8_BAR __builtin_amdgcn_s_barrier()
;     __device__ __forceinline__ void operator()(const f32x4 (&acc)[2][2][4][2], const Unit& u, int wr, int wc, int fr_, int fq) const {
;     ...
;         bf16_t* Hblk = H + ((size_t)(u.pm * (ldh / BK) + 2 * u.pn + (wc >> 1)) * BM + wr * 64 + fr) * BK + (wc & 1) * 32 + 8 * fq;
; #pragma unroll
;         for (int ai = 0; ai < 2; ++ai)
; #pragma unroll
;             for (int m = 0; m < 4; ++m) {
;                 f32x4 v0, v1;
; #pragma unroll
;                 for (int j = 0; j < 4; ++j) { const float g0 = acc[ai][0][m][0][j], g1 = acc[ai][0][m][1][j];
;                     v0[j] = g0 * fast_sigmoid(g0) * acc[ai][1][m][0][j]; v1[j] = g1 * fast_sigmoid(g1) * acc[ai][1][m][1][j]; }
;                 *(u32x4*)(Hblk + (size_t)(ai * HALF + m * 16) * BK) = pack8(v0, v1); }
; template <class Epi, class Sched, bool ALIGN_EPI = false, bool SP2 = false, bool ABLK = false, bool BBLK = false>
; __device__ __forceinline__ void gemm_phase(PG8_LAS unsigned char* lds, const Gemm g, const Sched& S, const Epi& E) {
;     ...
;         if constexpr (ALIGN_EPI) { if (wr == 0) PG8_BAR; }
;         if constexpr (!Epi::AFTER_DRAIN) { E(acc, cur, wr, wc, fr, fq); S.done(cur); }
;         if (!has_next) break;
; #pragma unroll
;         for (int a = 0; a < 2; ++a)
; #pragma unroll
;             for (int b = 0; b < 2; ++b)
; #pragma unroll
;                 for (int m = 0; m < 4; ++m)
; #pragma unroll
;                     for (int n = 0; n < 2; ++n) acc[a][b][m][n] = (f32x4){0.f, 0.f, 0.f, 0.f};
;         cur = nxt; cA = nA; cB = nB; ++ui;
;         if constexpr (ALIGN_EPI) { if (wr == 1) PG8_BAR; }
;     }
.LBB0_219:
	v_pk_mul_f32 v[190:191], v[62:63], v[184:185]
	v_pk_mul_f32 v[192:193], v[64:65], v[184:185]
	v_pk_mul_f32 v[224:225], v[54:55], v[184:185]
	v_pk_mul_f32 v[226:227], v[56:57], v[184:185]
	v_exp_f32_e32 v190, v190
	v_exp_f32_e32 v191, v191
	v_exp_f32_e32 v192, v192
	v_exp_f32_e32 v193, v193
	v_exp_f32_e32 v224, v224
	v_exp_f32_e32 v225, v225
	v_exp_f32_e32 v226, v226
	v_exp_f32_e32 v227, v227
	v_pk_add_f32 v[190:191], v[190:191], v[188:189]
	v_pk_add_f32 v[192:193], v[192:193], v[188:189]
	v_pk_add_f32 v[224:225], v[224:225], v[188:189]
	v_pk_add_f32 v[226:227], v[226:227], v[188:189]
	v_rcp_f32_e32 v190, v190
	v_rcp_f32_e32 v191, v191
	v_rcp_f32_e32 v192, v192
	v_rcp_f32_e32 v193, v193
	v_rcp_f32_e32 v224, v224
	v_rcp_f32_e32 v225, v225
	v_rcp_f32_e32 v226, v226
	v_rcp_f32_e32 v227, v227
	v_pk_mul_f32 v[62:63], v[62:63], v[190:191]
	v_pk_mul_f32 v[64:65], v[64:65], v[192:193]
	v_pk_mul_f32 v[54:55], v[54:55], v[224:225]
	v_pk_mul_f32 v[56:57], v[56:57], v[226:227]
	v_pk_mul_f32 v[62:63], v[62:63], v[58:59]
	v_pk_mul_f32 v[64:65], v[64:65], v[60:61]
	v_pk_mul_f32 v[54:55], v[54:55], v[50:51]
	v_pk_mul_f32 v[56:57], v[56:57], v[52:53]
	v_cvt_pk_bf16_f32 v52, v62, v63
	v_cvt_pk_bf16_f32 v53, v64, v65
	v_cvt_pk_bf16_f32 v54, v54, v55
	v_cvt_pk_bf16_f32 v55, v56, v57
	v_add_co_u32_e32 v56, vcc, s87, v142
	s_nop 1
	v_addc_co_u32_e32 v57, vcc, 0, v143, vcc
	v_add_co_u32_e32 v50, vcc, s0, v142
	s_nop 1
	s_mov_b64 s[0:1], -1
	v_addc_co_u32_e32 v51, vcc, 0, v143, vcc
	global_store_dwordx4 v[50:51], v[52:55], off offset:-4096
	v_pk_mul_f32 v[190:191], v[46:47], v[184:185]
	v_pk_mul_f32 v[192:193], v[48:49], v[184:185]
	v_pk_mul_f32 v[224:225], v[38:39], v[184:185]
	v_pk_mul_f32 v[226:227], v[40:41], v[184:185]
	v_exp_f32_e32 v190, v190
	v_exp_f32_e32 v191, v191
	v_exp_f32_e32 v192, v192
	v_exp_f32_e32 v193, v193
	v_exp_f32_e32 v224, v224
	v_exp_f32_e32 v225, v225
	v_exp_f32_e32 v226, v226
	v_exp_f32_e32 v227, v227
	v_pk_add_f32 v[190:191], v[190:191], v[188:189]
	v_pk_add_f32 v[192:193], v[192:193], v[188:189]
	v_pk_add_f32 v[224:225], v[224:225], v[188:189]
	v_pk_add_f32 v[226:227], v[226:227], v[188:189]
	v_rcp_f32_e32 v190, v190
	v_rcp_f32_e32 v191, v191
	v_rcp_f32_e32 v192, v192
	v_rcp_f32_e32 v193, v193
	v_rcp_f32_e32 v224, v224
	v_rcp_f32_e32 v225, v225
	v_rcp_f32_e32 v226, v226
	v_rcp_f32_e32 v227, v227
	v_pk_mul_f32 v[46:47], v[46:47], v[190:191]
	v_pk_mul_f32 v[48:49], v[48:49], v[192:193]
	v_pk_mul_f32 v[38:39], v[38:39], v[224:225]
	v_pk_mul_f32 v[40:41], v[40:41], v[226:227]
	v_pk_mul_f32 v[46:47], v[46:47], v[42:43]
	v_pk_mul_f32 v[48:49], v[48:49], v[44:45]
	v_pk_mul_f32 v[38:39], v[38:39], v[34:35]
	v_pk_mul_f32 v[40:41], v[40:41], v[36:37]
	v_cvt_pk_bf16_f32 v34, v46, v47
	v_cvt_pk_bf16_f32 v35, v48, v49
	v_cvt_pk_bf16_f32 v36, v38, v39
	v_cvt_pk_bf16_f32 v37, v40, v41
	s_andn2_b64 vcc, exec, s[4:5]
	global_store_dwordx4 v[56:57], v[34:37], off offset:2048
	v_pk_mul_f32 v[190:191], v[30:31], v[184:185]
	v_pk_mul_f32 v[192:193], v[32:33], v[184:185]
	v_pk_mul_f32 v[224:225], v[22:23], v[184:185]
	v_pk_mul_f32 v[226:227], v[24:25], v[184:185]
	v_exp_f32_e32 v190, v190
	v_exp_f32_e32 v191, v191
	v_exp_f32_e32 v192, v192
	v_exp_f32_e32 v193, v193
	v_exp_f32_e32 v224, v224
	v_exp_f32_e32 v225, v225
	v_exp_f32_e32 v226, v226
	v_exp_f32_e32 v227, v227
	v_pk_add_f32 v[190:191], v[190:191], v[188:189]
	v_pk_add_f32 v[192:193], v[192:193], v[188:189]
	v_pk_add_f32 v[224:225], v[224:225], v[188:189]
	v_pk_add_f32 v[226:227], v[226:227], v[188:189]
	v_rcp_f32_e32 v190, v190
	v_rcp_f32_e32 v191, v191
	v_rcp_f32_e32 v192, v192
	v_rcp_f32_e32 v193, v193
	v_rcp_f32_e32 v224, v224
	v_rcp_f32_e32 v225, v225
	v_rcp_f32_e32 v226, v226
	v_rcp_f32_e32 v227, v227
	v_pk_mul_f32 v[30:31], v[30:31], v[190:191]
	v_pk_mul_f32 v[32:33], v[32:33], v[192:193]
	v_pk_mul_f32 v[22:23], v[22:23], v[224:225]
	v_pk_mul_f32 v[24:25], v[24:25], v[226:227]
	v_pk_mul_f32 v[30:31], v[30:31], v[26:27]
	v_pk_mul_f32 v[32:33], v[32:33], v[28:29]
	v_pk_mul_f32 v[22:23], v[22:23], v[18:19]
	v_pk_mul_f32 v[24:25], v[24:25], v[20:21]
	v_cvt_pk_bf16_f32 v18, v30, v31
	v_cvt_pk_bf16_f32 v19, v32, v33
	v_cvt_pk_bf16_f32 v20, v22, v23
	v_cvt_pk_bf16_f32 v21, v24, v25
	global_store_dwordx4 v[50:51], v[18:21], off
	v_pk_mul_f32 v[190:191], v[14:15], v[184:185]
	v_pk_mul_f32 v[192:193], v[16:17], v[184:185]
	v_pk_mul_f32 v[224:225], v[6:7], v[184:185]
	v_pk_mul_f32 v[226:227], v[8:9], v[184:185]
	v_exp_f32_e32 v190, v190
	v_exp_f32_e32 v191, v191
	v_exp_f32_e32 v192, v192
	v_exp_f32_e32 v193, v193
	v_exp_f32_e32 v224, v224
	v_exp_f32_e32 v225, v225
	v_exp_f32_e32 v226, v226
	v_exp_f32_e32 v227, v227
	v_pk_add_f32 v[190:191], v[190:191], v[188:189]
	v_pk_add_f32 v[192:193], v[192:193], v[188:189]
	v_pk_add_f32 v[224:225], v[224:225], v[188:189]
	v_pk_add_f32 v[226:227], v[226:227], v[188:189]
	v_rcp_f32_e32 v190, v190
	v_rcp_f32_e32 v191, v191
	v_rcp_f32_e32 v192, v192
	v_rcp_f32_e32 v193, v193
	v_rcp_f32_e32 v224, v224
	v_rcp_f32_e32 v225, v225
	v_rcp_f32_e32 v226, v226
	v_rcp_f32_e32 v227, v227
	v_pk_mul_f32 v[14:15], v[14:15], v[190:191]
	v_pk_mul_f32 v[16:17], v[16:17], v[192:193]
	v_pk_mul_f32 v[6:7], v[6:7], v[224:225]
	v_pk_mul_f32 v[8:9], v[8:9], v[226:227]
	v_pk_mul_f32 v[14:15], v[14:15], v[10:11]
	v_pk_mul_f32 v[16:17], v[16:17], v[12:13]
	v_pk_mul_f32 v[6:7], v[6:7], v[2:3]
	v_pk_mul_f32 v[8:9], v[8:9], v[4:5]
	v_cvt_pk_bf16_f32 v2, v14, v15
	v_cvt_pk_bf16_f32 v3, v16, v17
	v_cvt_pk_bf16_f32 v4, v6, v7
	v_cvt_pk_bf16_f32 v5, v8, v9
	global_store_dwordx4 v[50:51], v[2:5], off offset:2048
	s_cbranch_vccnz .LBB0_212
	s_andn2_b64 vcc, exec, s[6:7]
	s_cbranch_vccnz .LBB0_211
	s_barrier
	s_branch .LBB0_211

; #define PG8_STAGE(bufoff, gbase, voff) do { _Pragma("unroll") for (int _i = 0; _i < 2; ++_i) \
;         __builtin_amdgcn_global_load_lds((const unsigned*)((const char*)(gbase) + (voff)[_i]), (PG8_LAS unsigned*)(lds + (bufoff) + ldsw + _i * 8192), 16, 0, 0); } while (0)
; #define PG8_LDA(dst, b, h) do { _Pragma("unroll") for (int m = 0; m < 4; ++m) _Pragma("unroll") for (int k = 0; k < 2; ++k) dst[m][k] = *(const PG8_LAS bf16x8*)(lds + PG8_SA(b, h) + aoff + m * 2048 + k * 1024); } while (0)
; #define PG8_WAIT_V(n) asm volatile("s_waitcnt vmcnt(" #n ")" ::: "memory")
; #define PG8_WAIT_L(n) asm volatile("s_waitcnt lgkmcnt(" #n ")" ::: "memory")
; template <class Epi, class Sched, bool ALIGN_EPI = false, bool SP2 = false, bool ABLK = false, bool BBLK = false>
; __device__ __forceinline__ void gemm_phase(PG8_LAS unsigned char* lds, const Gemm g, const Sched& S, const Epi& E) {
;     ...
;         for (int t = 0; t < nt; t += 2) {
;             const bool last = (t == nt - 2);
;             const char* a1 = cA + (size_t)(t + 1) * kstepA;
;             const char* a2 = last ? nA : cA + (size_t)(t + 2) * kstepA; const char* b2 = last ? nB : cB + (size_t)(t + 2) * kstepB;
;             const char* a3 = a2 + kstepA; const char* b3 = b2 + kstepB;
;             if (last && has_next) S.a_ready(nxt);
;             if constexpr (SP2) {
;             PG8_LDB(B0, 0, 0); PG8_LDB(B1, 0, 1); PG8_SCHED; PG8_LDA(At, 0, 0); PG8_STAGE(PG8_SA(1, 1), a1 + hstepA, voffA);
;             PG8_WAIT_V(8); PG8_WAIT_L(0); PG8_BAR; PG8_MMA(0, 0, At, B0); PG8_MMA(0, 1, At, B1); PG8_BAR; PG8_SCHED;
;             PG8_LDA(At, 0, 1); PG8_STAGE(PG8_SB(0, 0), b2, voffB); PG8_STAGE(PG8_SB(0, 1), b2 + hstepB, voffB); PG8_STAGE(PG8_SA(0, 0), a2, voffA);
;             PG8_WAIT_V(8); PG8_WAIT_L(0); PG8_BAR; PG8_MMA(1, 0, At, B0); PG8_MMA(1, 1, At, B1); PG8_BAR; PG8_SCHED;
;             PG8_LDB(B0, 1, 0); PG8_LDB(B1, 1, 1); PG8_SCHED; PG8_LDA(At, 1, 0); PG8_STAGE(PG8_SA(0, 1), a2 + hstepA, voffA);
;             PG8_WAIT_V(8); PG8_WAIT_L(0); PG8_BAR; PG8_MMA(0, 0, At, B0); PG8_MMA(0, 1, At, B1); PG8_BAR; PG8_SCHED;
;             PG8_LDA(At, 1, 1); PG8_STAGE(PG8_SB(1, 0), b3, voffB); PG8_STAGE(PG8_SB(1, 1), b3 + hstepB, voffB); PG8_STAGE(PG8_SA(1, 0), a3, voffA);
;             PG8_WAIT_V(8); PG8_WAIT_L(0); PG8_BAR; PG8_MMA(1, 0, At, B0); PG8_MMA(1, 1, At, B1); PG8_BAR; PG8_SCHED;
.Lmid_1340:
	s_add_i32 s52, 0, 0x18000
	v_add_u32_e32 v142, s52, v145
	s_add_i32 s75, 0, 0x1c000
	ds_read_b128 v[148:151], v142
	ds_read_b128 v[152:155], v142 offset:1024
	ds_read_b128 v[156:159], v142 offset:2048
	ds_read_b128 v[160:163], v142 offset:3072
	v_add_u32_e32 v142, s75, v145
	ds_read_b128 v[164:167], v142
	ds_read_b128 v[168:171], v142 offset:1024
	ds_read_b128 v[172:175], v142 offset:2048
	ds_read_b128 v[176:179], v142 offset:3072
	s_add_u32 s34, s34, 0x4000
	s_addc_u32 s35, s35, 0
	s_mov_b32 m0, s47
	v_lshl_add_u64 v[142:143], s[34:35], 0, v[136:137]
	ds_read_b128 v[180:183], v146 offset:32768
	ds_read_b128 v[196:199], v146 offset:33792
	ds_read_b128 v[200:203], v146 offset:34816
	ds_read_b128 v[204:207], v146 offset:35840
	ds_read_b128 v[208:211], v146 offset:36864
	ds_read_b128 v[212:215], v146 offset:37888
	ds_read_b128 v[216:219], v146 offset:38912
	ds_read_b128 v[220:223], v146 offset:39936
	global_load_lds_dwordx4 v[142:143], off
	v_lshl_add_u64 v[142:143], s[34:35], 0, v[132:133]
	s_mov_b32 m0, s50
	s_nop 0
	global_load_lds_dwordx4 v[142:143], off
	s_waitcnt vmcnt(8)
	s_waitcnt lgkmcnt(0)
	s_barrier
	s_setprio 1
	s_waitcnt lgkmcnt(0)
	v_mfma_f32_16x16x32_bf16 v[126:129], v[148:151], v[180:183], v[126:129]
	v_mfma_f32_16x16x32_bf16 v[118:121], v[156:159], v[180:183], v[118:121]
	v_mfma_f32_16x16x32_bf16 v[110:113], v[148:151], v[200:203], v[110:113]
	v_mfma_f32_16x16x32_bf16 v[102:105], v[156:159], v[200:203], v[102:105]
	v_mfma_f32_16x16x32_bf16 v[94:97], v[148:151], v[208:211], v[94:97]
	v_mfma_f32_16x16x32_bf16 v[86:89], v[156:159], v[208:211], v[86:89]
	v_mfma_f32_16x16x32_bf16 v[78:81], v[148:151], v[216:219], v[78:81]
	v_mfma_f32_16x16x32_bf16 v[70:73], v[156:159], v[216:219], v[70:73]
	v_mfma_f32_16x16x32_bf16 v[126:129], v[152:155], v[196:199], v[126:129]
	v_mfma_f32_16x16x32_bf16 v[118:121], v[160:163], v[196:199], v[118:121]
	v_mfma_f32_16x16x32_bf16 v[110:113], v[152:155], v[204:207], v[110:113]
	v_mfma_f32_16x16x32_bf16 v[102:105], v[160:163], v[204:207], v[102:105]
	v_mfma_f32_16x16x32_bf16 v[94:97], v[152:155], v[212:215], v[94:97]
	v_mfma_f32_16x16x32_bf16 v[86:89], v[160:163], v[212:215], v[86:89]
	v_mfma_f32_16x16x32_bf16 v[78:81], v[152:155], v[220:223], v[78:81]
	v_mfma_f32_16x16x32_bf16 v[70:73], v[160:163], v[220:223], v[70:73]
	s_setprio 0
	s_setprio 1
	v_mfma_f32_16x16x32_bf16 v[122:125], v[164:167], v[180:183], v[122:125]
	v_mfma_f32_16x16x32_bf16 v[114:117], v[172:175], v[180:183], v[114:117]
	v_mfma_f32_16x16x32_bf16 v[106:109], v[164:167], v[200:203], v[106:109]
	v_mfma_f32_16x16x32_bf16 v[98:101], v[172:175], v[200:203], v[98:101]
	v_mfma_f32_16x16x32_bf16 v[90:93], v[164:167], v[208:211], v[90:93]
	v_mfma_f32_16x16x32_bf16 v[82:85], v[172:175], v[208:211], v[82:85]
	v_mfma_f32_16x16x32_bf16 v[74:77], v[164:167], v[216:219], v[74:77]
	v_mfma_f32_16x16x32_bf16 v[66:69], v[172:175], v[216:219], v[66:69]
	v_mfma_f32_16x16x32_bf16 v[122:125], v[168:171], v[196:199], v[122:125]
	v_mfma_f32_16x16x32_bf16 v[114:117], v[176:179], v[196:199], v[114:117]
	v_mfma_f32_16x16x32_bf16 v[106:109], v[168:171], v[204:207], v[106:109]
	v_mfma_f32_16x16x32_bf16 v[98:101], v[176:179], v[204:207], v[98:101]
	v_mfma_f32_16x16x32_bf16 v[90:93], v[168:171], v[212:215], v[90:93]
	v_mfma_f32_16x16x32_bf16 v[82:85], v[176:179], v[212:215], v[82:85]
	v_mfma_f32_16x16x32_bf16 v[74:77], v[168:171], v[220:223], v[74:77]
	v_mfma_f32_16x16x32_bf16 v[66:69], v[176:179], v[220:223], v[66:69]
	s_setprio 0
	s_barrier
	s_add_u32 s34, s30, 0x8000
	s_addc_u32 s35, s31, 0
	s_add_i32 s52, s52, s44
	v_lshl_add_u64 v[142:143], s[34:35], 0, v[134:135]
	s_mov_b32 m0, s52
	ds_read_b128 v[180:183], v146 offset:49152
	ds_read_b128 v[196:199], v146 offset:50176
	ds_read_b128 v[200:203], v146 offset:51200
	ds_read_b128 v[204:207], v146 offset:52224
	ds_read_b128 v[208:211], v146 offset:53248
	ds_read_b128 v[212:215], v146 offset:54272
	ds_read_b128 v[216:219], v146 offset:55296
	ds_read_b128 v[220:223], v146 offset:56320
	global_load_lds_dwordx4 v[142:143], off
	s_add_i32 m0, s52, 0x2000
	s_add_u32 s30, s30, 0xc000
	v_lshl_add_u64 v[142:143], s[34:35], 0, v[130:131]
	s_addc_u32 s31, s31, 0
	s_add_i32 s34, s75, s44
	global_load_lds_dwordx4 v[142:143], off
	v_lshl_add_u64 v[142:143], s[30:31], 0, v[134:135]
	s_mov_b32 m0, s34
	s_nop 0
	global_load_lds_dwordx4 v[142:143], off
	v_lshl_add_u64 v[142:143], s[30:31], 0, v[130:131]
	s_add_i32 m0, s34, 0x2000
	s_nop 0
	global_load_lds_dwordx4 v[142:143], off
	v_lshl_add_u64 v[142:143], s[28:29], 0, v[136:137]
	s_mov_b32 m0, s56
	s_nop 0
	global_load_lds_dwordx4 v[142:143], off
	v_lshl_add_u64 v[142:143], s[28:29], 0, v[132:133]
	s_mov_b32 m0, s60
	s_nop 0
	global_load_lds_dwordx4 v[142:143], off
	s_cmp_eq_u32 s83, 28
	s_cbranch_scc1 .Llast_1340
	s_waitcnt vmcnt(8)
	s_waitcnt lgkmcnt(0)
	s_barrier
; __device__ __forceinline__ float fast_sigmoid(float x) { return __builtin_amdgcn_rcpf(1.0f + __builtin_amdgcn_exp2f(-1.4426950408889634f * x)); }
; __device__ __forceinline__ u32x4 pack8(const f32x4 v0, const f32x4 v1) { u32x4 w; w.x = cvt_pk_bf16(v0[0], v0[1]); w.y = cvt_pk_bf16(v0[2], v0[3]); w.z = cvt_pk_bf16(v1[0], v1[1]); w.w = cvt_pk_bf16(v1[2], v1[3]); return w; }
; #define PG8_STAGE(bufoff, gbase, voff) do { _Pragma("unroll") for (int _i = 0; _i < 2; ++_i) \
;         __builtin_amdgcn_global_load_lds((const unsigned*)((const char*)(gbase) + (voff)[_i]), (PG8_LAS unsigned*)(lds + (bufoff) + ldsw + _i * 8192), 16, 0, 0); } while (0)
; #define PG8_LDA(dst, b, h) do { _Pragma("unroll") for (int m = 0; m < 4; ++m) _Pragma("unroll") for (int k = 0; k < 2; ++k) dst[m][k] = *(const PG8_LAS bf16x8*)(lds + PG8_SA(b, h) + aoff + m * 2048 + k * 1024); } while (0)
; #define PG8_WAIT_V(n) asm volatile("s_waitcnt vmcnt(" #n ")" ::: "memory")
; #define PG8_BAR __builtin_amdgcn_s_barrier()
;     __device__ __forceinline__ void operator()(const f32x4 (&acc)[2][2][4][2], const Unit& u, int wr, int wc, int fr_, int fq) const {
;     ...
;         bf16_t* Hblk = H + ((size_t)(u.pm * (ldh / BK) + 2 * u.pn + (wc >> 1)) * BM + wr * 64 + fr) * BK + (wc & 1) * 32 + 8 * fq;
; #pragma unroll
;         for (int ai = 0; ai < 2; ++ai)
; #pragma unroll
;             for (int m = 0; m < 4; ++m) {
;                 f32x4 v0, v1;
; #pragma unroll
;                 for (int j = 0; j < 4; ++j) { const float g0 = acc[ai][0][m][0][j], g1 = acc[ai][0][m][1][j];
;                     v0[j] = g0 * fast_sigmoid(g0) * acc[ai][1][m][0][j]; v1[j] = g1 * fast_sigmoid(g1) * acc[ai][1][m][1][j]; }
;                 *(u32x4*)(Hblk + (size_t)(ai * HALF + m * 16) * BK) = pack8(v0, v1); }
; template <class Epi, class Sched, bool ALIGN_EPI = false, bool SP2 = false, bool ABLK = false, bool BBLK = false>
; __device__ __forceinline__ void gemm_phase(PG8_LAS unsigned char* lds, const Gemm g, const Sched& S, const Epi& E) {
;     ...
;             PG8_WAIT_V(8); PG8_WAIT_L(0); PG8_BAR; PG8_MMA(0, 0, At, B0); PG8_MMA(0, 1, At, B1); PG8_BAR; PG8_SCHED;
;             PG8_LDA(At, 1, 1); PG8_STAGE(PG8_SB(1, 0), b3, voffB); PG8_STAGE(PG8_SB(1, 1), b3 + hstepB, voffB); PG8_STAGE(PG8_SA(1, 0), a3, voffA);
;             PG8_WAIT_V(8); PG8_WAIT_L(0); PG8_BAR; PG8_MMA(1, 0, At, B0); PG8_MMA(1, 1, At, B1); PG8_BAR; PG8_SCHED;
	s_setprio 1
	s_waitcnt lgkmcnt(0)
	v_mfma_f32_16x16x32_bf16 v[62:65], v[148:151], v[180:183], v[62:65]
	v_mfma_f32_16x16x32_bf16 v[54:57], v[156:159], v[180:183], v[54:57]
	v_mfma_f32_16x16x32_bf16 v[46:49], v[148:151], v[200:203], v[46:49]
	v_mfma_f32_16x16x32_bf16 v[38:41], v[156:159], v[200:203], v[38:41]
	v_mfma_f32_16x16x32_bf16 v[30:33], v[148:151], v[208:211], v[30:33]
	v_mfma_f32_16x16x32_bf16 v[22:25], v[156:159], v[208:211], v[22:25]
	v_mfma_f32_16x16x32_bf16 v[14:17], v[148:151], v[216:219], v[14:17]
	v_mfma_f32_16x16x32_bf16 v[6:9], v[156:159], v[216:219], v[6:9]
	v_mfma_f32_16x16x32_bf16 v[62:65], v[152:155], v[196:199], v[62:65]
	v_mfma_f32_16x16x32_bf16 v[54:57], v[160:163], v[196:199], v[54:57]
	v_mfma_f32_16x16x32_bf16 v[46:49], v[152:155], v[204:207], v[46:49]
	v_mfma_f32_16x16x32_bf16 v[38:41], v[160:163], v[204:207], v[38:41]
	v_mfma_f32_16x16x32_bf16 v[30:33], v[152:155], v[212:215], v[30:33]
	v_mfma_f32_16x16x32_bf16 v[22:25], v[160:163], v[212:215], v[22:25]
	v_mfma_f32_16x16x32_bf16 v[14:17], v[152:155], v[220:223], v[14:17]
	v_mfma_f32_16x16x32_bf16 v[6:9], v[160:163], v[220:223], v[6:9]
	s_setprio 0
	s_setprio 1
	v_mfma_f32_16x16x32_bf16 v[58:61], v[164:167], v[180:183], v[58:61]
	v_mfma_f32_16x16x32_bf16 v[50:53], v[172:175], v[180:183], v[50:53]
	v_mfma_f32_16x16x32_bf16 v[42:45], v[164:167], v[200:203], v[42:45]
	v_mfma_f32_16x16x32_bf16 v[34:37], v[172:175], v[200:203], v[34:37]
	v_mfma_f32_16x16x32_bf16 v[26:29], v[164:167], v[208:211], v[26:29]
	v_mfma_f32_16x16x32_bf16 v[18:21], v[172:175], v[208:211], v[18:21]
	v_mfma_f32_16x16x32_bf16 v[10:13], v[164:167], v[216:219], v[10:13]
	v_mfma_f32_16x16x32_bf16 v[2:5], v[172:175], v[216:219], v[2:5]
	v_mfma_f32_16x16x32_bf16 v[58:61], v[168:171], v[196:199], v[58:61]
	v_mfma_f32_16x16x32_bf16 v[50:53], v[176:179], v[196:199], v[50:53]
	v_mfma_f32_16x16x32_bf16 v[42:45], v[168:171], v[204:207], v[42:45]
	v_mfma_f32_16x16x32_bf16 v[34:37], v[176:179], v[204:207], v[34:37]
	v_mfma_f32_16x16x32_bf16 v[26:29], v[168:171], v[212:215], v[26:29]
	v_mfma_f32_16x16x32_bf16 v[18:21], v[176:179], v[212:215], v[18:21]
	v_mfma_f32_16x16x32_bf16 v[10:13], v[168:171], v[220:223], v[10:13]
	v_mfma_f32_16x16x32_bf16 v[2:5], v[176:179], v[220:223], v[2:5]
	s_setprio 0
	s_barrier
	s_add_i32 s83, s83, 2
	s_add_u32 s26, s26, 0x10000
	s_addc_u32 s27, s27, 0
	s_add_u32 s73, s73, 0x10000
	s_addc_u32 s81, s81, 0
	s_cmp_gt_u32 s83, 29
	s_cbranch_scc0 .LBB0_1340
	s_branch .Lpost_1340
.Llast_1340:
	s_waitcnt vmcnt(8)
	s_waitcnt lgkmcnt(0)
	s_barrier
	s_setprio 1
	s_waitcnt lgkmcnt(0)
	v_mfma_f32_16x16x32_bf16 v[62:65], v[148:151], v[180:183], v[62:65]
	v_mov_b32_e32 v184, 0xbfb8aa3b
	v_mov_b32_e32 v185, 0xbfb8aa3b
	v_mov_b32_e32 v188, 1.0
	v_mov_b32_e32 v189, 1.0
	v_pk_mul_f32 v[190:191], v[126:127], v[184:185]
	v_pk_mul_f32 v[192:193], v[128:129], v[184:185]
	v_mfma_f32_16x16x32_bf16 v[54:57], v[156:159], v[180:183], v[54:57]
	v_pk_mul_f32 v[224:225], v[118:119], v[184:185]
	v_pk_mul_f32 v[226:227], v[120:121], v[184:185]
	v_exp_f32_e32 v190, v190
	v_exp_f32_e32 v191, v191
	v_exp_f32_e32 v192, v192
	v_exp_f32_e32 v193, v193
	v_mfma_f32_16x16x32_bf16 v[46:49], v[148:151], v[200:203], v[46:49]
	v_exp_f32_e32 v224, v224
	v_exp_f32_e32 v225, v225
	v_exp_f32_e32 v226, v226
	v_exp_f32_e32 v227, v227
	v_pk_add_f32 v[190:191], v[190:191], v[188:189]
	v_pk_add_f32 v[192:193], v[192:193], v[188:189]
	v_mfma_f32_16x16x32_bf16 v[38:41], v[156:159], v[200:203], v[38:41]
	v_pk_add_f32 v[224:225], v[224:225], v[188:189]
	v_pk_add_f32 v[226:227], v[226:227], v[188:189]
	v_rcp_f32_e32 v190, v190
	v_rcp_f32_e32 v191, v191
	v_rcp_f32_e32 v192, v192
	v_rcp_f32_e32 v193, v193
	v_mfma_f32_16x16x32_bf16 v[30:33], v[148:151], v[208:211], v[30:33]
	v_rcp_f32_e32 v224, v224
	v_rcp_f32_e32 v225, v225
	v_rcp_f32_e32 v226, v226
	v_rcp_f32_e32 v227, v227
	v_pk_mul_f32 v[126:127], v[126:127], v[190:191]
	v_pk_mul_f32 v[128:129], v[128:129], v[192:193]
	v_mfma_f32_16x16x32_bf16 v[22:25], v[156:159], v[208:211], v[22:25]
	v_pk_mul_f32 v[118:119], v[118:119], v[224:225]
	v_pk_mul_f32 v[120:121], v[120:121], v[226:227]
	v_pk_mul_f32 v[126:127], v[126:127], v[122:123]
	v_pk_mul_f32 v[128:129], v[128:129], v[124:125]
	v_pk_mul_f32 v[118:119], v[118:119], v[114:115]
	v_pk_mul_f32 v[120:121], v[120:121], v[116:117]
	v_mfma_f32_16x16x32_bf16 v[14:17], v[148:151], v[216:219], v[14:17]
	v_cvt_pk_bf16_f32 v114, v126, v127
	v_cvt_pk_bf16_f32 v115, v128, v129
	v_cvt_pk_bf16_f32 v116, v118, v119
	v_cvt_pk_bf16_f32 v117, v120, v121
	s_lshl_b32 s0, s0, 1
	s_mul_i32 s1, s24, 0x58
	v_mfma_f32_16x16x32_bf16 v[6:9], v[156:159], v[216:219], v[6:9]
	s_or_b32 s0, s0, s61
	s_add_i32 s0, s0, s1
	v_mov_b32_e32 v142, v144
	s_ashr_i32 s1, s0, 31
	s_lshl_b64 s[0:1], s[0:1], 15
	v_ashrrev_i32_e32 v143, 31, v142
	v_mfma_f32_16x16x32_bf16 v[62:65], v[152:155], v[196:199], v[62:65]
	v_lshl_add_u64 v[142:143], v[142:143], 0, s[8:9]
	s_add_u32 s0, s51, s0
	v_lshlrev_b64 v[142:143], 7, v[142:143]
	s_addc_u32 s1, s53, s1
	v_lshl_add_u64 v[142:143], s[0:1], 0, v[142:143]
	v_lshl_add_u64 v[142:143], v[142:143], 0, s[16:17]
	v_mfma_f32_16x16x32_bf16 v[54:57], v[160:163], v[196:199], v[54:57]
	v_lshl_add_u64 v[142:143], v[142:143], 0, v[186:187]
	s_movk_i32 s0, 0x5000
	s_mov_b32 s88, 0xf800000
	s_movk_i32 s89, 0xffe0
	s_mov_b32 s52, 0x80000
	global_store_dwordx4 v[142:143], v[114:117], off
	v_mfma_f32_16x16x32_bf16 v[46:49], v[152:155], v[204:207], v[46:49]
	v_pk_mul_f32 v[190:191], v[110:111], v[184:185]
	v_pk_mul_f32 v[192:193], v[112:113], v[184:185]
	v_pk_mul_f32 v[224:225], v[102:103], v[184:185]
	v_pk_mul_f32 v[226:227], v[104:105], v[184:185]
; __device__ __forceinline__ float fast_sigmoid(float x) { return __builtin_amdgcn_rcpf(1.0f + __builtin_amdgcn_exp2f(-1.4426950408889634f * x)); }
; __device__ __forceinline__ u32x4 pack8(const f32x4 v0, const f32x4 v1) { u32x4 w; w.x = cvt_pk_bf16(v0[0], v0[1]); w.y = cvt_pk_bf16(v0[2], v0[3]); w.z = cvt_pk_bf16(v1[0], v1[1]); w.w = cvt_pk_bf16(v1[2], v1[3]); return w; }
; #define PG8_MMA(ai, bj, At, Bt) do { __builtin_amdgcn_s_setprio(1); _Pragma("unroll") for (int m = 0; m < 4; ++m) _Pragma("unroll") for (int n = 0; n < 2; ++n) _Pragma("unroll") for (int k = 0; k < 2; ++k) \
;         acc[ai][bj][m][n] = __builtin_amdgcn_mfma_f32_16x16x32_bf16(Bt[n][k], At[m][k], acc[ai][bj][m][n], 0, 0, 0); __builtin_amdgcn_s_setprio(0); } while (0)
; #define PG8_WAIT_V(n) asm volatile("s_waitcnt vmcnt(" #n ")" ::: "memory")
; #define PG8_WAIT_L(n) asm volatile("s_waitcnt lgkmcnt(" #n ")" ::: "memory")
; #define PG8_BAR __builtin_amdgcn_s_barrier()
; #define PG8_SCHED __builtin_amdgcn_sched_barrier(0)
;     __device__ __forceinline__ void operator()(const f32x4 (&acc)[2][2][4][2], const Unit& u, int wr, int wc, int fr_, int fq) const {
;     ...
;                 for (int j = 0; j < 4; ++j) { const float g0 = acc[ai][0][m][0][j], g1 = acc[ai][0][m][1][j];
;                     v0[j] = g0 * fast_sigmoid(g0) * acc[ai][1][m][0][j]; v1[j] = g1 * fast_sigmoid(g1) * acc[ai][1][m][1][j]; }
;                 *(u32x4*)(Hblk + (size_t)(ai * HALF + m * 16) * BK) = pack8(v0, v1); }
; template <class Epi, class Sched, bool ALIGN_EPI = false, bool SP2 = false, bool ABLK = false, bool BBLK = false>
; __device__ __forceinline__ void gemm_phase(PG8_LAS unsigned char* lds, const Gemm g, const Sched& S, const Epi& E) {
;     ...
;             PG8_WAIT_V(8); PG8_WAIT_L(0); PG8_BAR; PG8_MMA(1, 0, At, B0); PG8_MMA(1, 1, At, B1); PG8_BAR; PG8_SCHED;
	v_exp_f32_e32 v190, v190
	v_exp_f32_e32 v191, v191
	v_mfma_f32_16x16x32_bf16 v[38:41], v[160:163], v[204:207], v[38:41]
	v_exp_f32_e32 v192, v192
	v_exp_f32_e32 v193, v193
	v_exp_f32_e32 v224, v224
	v_exp_f32_e32 v225, v225
	v_exp_f32_e32 v226, v226
	v_exp_f32_e32 v227, v227
	v_mfma_f32_16x16x32_bf16 v[30:33], v[152:155], v[212:215], v[30:33]
	v_pk_add_f32 v[190:191], v[190:191], v[188:189]
	v_pk_add_f32 v[192:193], v[192:193], v[188:189]
	v_pk_add_f32 v[224:225], v[224:225], v[188:189]
	v_pk_add_f32 v[226:227], v[226:227], v[188:189]
	v_rcp_f32_e32 v190, v190
	v_rcp_f32_e32 v191, v191
	v_mfma_f32_16x16x32_bf16 v[22:25], v[160:163], v[212:215], v[22:25]
	v_rcp_f32_e32 v192, v192
	v_rcp_f32_e32 v193, v193
	v_rcp_f32_e32 v224, v224
	v_rcp_f32_e32 v225, v225
	v_rcp_f32_e32 v226, v226
	v_rcp_f32_e32 v227, v227
	v_mfma_f32_16x16x32_bf16 v[14:17], v[152:155], v[220:223], v[14:17]
	v_pk_mul_f32 v[110:111], v[110:111], v[190:191]
	v_pk_mul_f32 v[112:113], v[112:113], v[192:193]
	v_pk_mul_f32 v[102:103], v[102:103], v[224:225]
	v_pk_mul_f32 v[104:105], v[104:105], v[226:227]
	v_pk_mul_f32 v[110:111], v[110:111], v[106:107]
	v_pk_mul_f32 v[112:113], v[112:113], v[108:109]
	v_mfma_f32_16x16x32_bf16 v[6:9], v[160:163], v[220:223], v[6:9]
	v_pk_mul_f32 v[102:103], v[102:103], v[98:99]
	v_pk_mul_f32 v[104:105], v[104:105], v[100:101]
	v_cvt_pk_bf16_f32 v98, v110, v111
	v_cvt_pk_bf16_f32 v99, v112, v113
	v_cvt_pk_bf16_f32 v100, v102, v103
	v_cvt_pk_bf16_f32 v101, v104, v105
	s_setprio 0
	s_setprio 1
	v_mfma_f32_16x16x32_bf16 v[58:61], v[164:167], v[180:183], v[58:61]
	global_store_dwordx4 v[142:143], v[98:101], off offset:2048
	v_pk_mul_f32 v[190:191], v[94:95], v[184:185]
	v_pk_mul_f32 v[192:193], v[96:97], v[184:185]
	v_pk_mul_f32 v[224:225], v[86:87], v[184:185]
	v_pk_mul_f32 v[226:227], v[88:89], v[184:185]
	v_exp_f32_e32 v190, v190
	v_mfma_f32_16x16x32_bf16 v[50:53], v[172:175], v[180:183], v[50:53]
	v_exp_f32_e32 v191, v191
	v_exp_f32_e32 v192, v192
	v_exp_f32_e32 v193, v193
	v_exp_f32_e32 v224, v224
	v_exp_f32_e32 v225, v225
	v_exp_f32_e32 v226, v226
	v_mfma_f32_16x16x32_bf16 v[42:45], v[164:167], v[200:203], v[42:45]
	v_exp_f32_e32 v227, v227
	v_pk_add_f32 v[190:191], v[190:191], v[188:189]
	v_pk_add_f32 v[192:193], v[192:193], v[188:189]
	v_pk_add_f32 v[224:225], v[224:225], v[188:189]
	v_pk_add_f32 v[226:227], v[226:227], v[188:189]
	v_rcp_f32_e32 v190, v190
	v_mfma_f32_16x16x32_bf16 v[34:37], v[172:175], v[200:203], v[34:37]
	v_rcp_f32_e32 v191, v191
	v_rcp_f32_e32 v192, v192
	v_rcp_f32_e32 v193, v193
	v_rcp_f32_e32 v224, v224
	v_rcp_f32_e32 v225, v225
	v_rcp_f32_e32 v226, v226
	v_mfma_f32_16x16x32_bf16 v[26:29], v[164:167], v[208:211], v[26:29]
	v_rcp_f32_e32 v227, v227
	v_pk_mul_f32 v[94:95], v[94:95], v[190:191]
	v_pk_mul_f32 v[96:97], v[96:97], v[192:193]
	v_pk_mul_f32 v[86:87], v[86:87], v[224:225]
	v_pk_mul_f32 v[88:89], v[88:89], v[226:227]
	v_pk_mul_f32 v[94:95], v[94:95], v[90:91]
	v_mfma_f32_16x16x32_bf16 v[18:21], v[172:175], v[208:211], v[18:21]
	v_pk_mul_f32 v[96:97], v[96:97], v[92:93]
	v_pk_mul_f32 v[86:87], v[86:87], v[82:83]
	v_pk_mul_f32 v[88:89], v[88:89], v[84:85]
	v_cvt_pk_bf16_f32 v82, v94, v95
	v_cvt_pk_bf16_f32 v83, v96, v97
	v_cvt_pk_bf16_f32 v84, v86, v87
	v_mfma_f32_16x16x32_bf16 v[10:13], v[164:167], v[216:219], v[10:13]
	v_cvt_pk_bf16_f32 v85, v88, v89
	v_add_co_u32_e32 v86, vcc, s67, v142
	s_nop 1
	v_addc_co_u32_e32 v87, vcc, 0, v143, vcc
	global_store_dwordx4 v[86:87], v[82:85], off
	v_pk_mul_f32 v[190:191], v[78:79], v[184:185]
	v_mfma_f32_16x16x32_bf16 v[2:5], v[172:175], v[216:219], v[2:5]
	v_pk_mul_f32 v[192:193], v[80:81], v[184:185]
	v_pk_mul_f32 v[224:225], v[70:71], v[184:185]
	v_pk_mul_f32 v[226:227], v[72:73], v[184:185]
	v_exp_f32_e32 v190, v190
	v_exp_f32_e32 v191, v191
	v_exp_f32_e32 v192, v192
	v_mfma_f32_16x16x32_bf16 v[58:61], v[168:171], v[196:199], v[58:61]
	v_exp_f32_e32 v193, v193
	v_exp_f32_e32 v224, v224
	v_exp_f32_e32 v225, v225
	v_exp_f32_e32 v226, v226
	v_exp_f32_e32 v227, v227
	v_pk_add_f32 v[190:191], v[190:191], v[188:189]
	v_mfma_f32_16x16x32_bf16 v[50:53], v[176:179], v[196:199], v[50:53]
	v_pk_add_f32 v[192:193], v[192:193], v[188:189]
	v_pk_add_f32 v[224:225], v[224:225], v[188:189]
	v_pk_add_f32 v[226:227], v[226:227], v[188:189]
	v_rcp_f32_e32 v190, v190
	v_rcp_f32_e32 v191, v191
	v_rcp_f32_e32 v192, v192
	v_mfma_f32_16x16x32_bf16 v[42:45], v[168:171], v[204:207], v[42:45]
	v_rcp_f32_e32 v193, v193
	v_rcp_f32_e32 v224, v224
	v_rcp_f32_e32 v225, v225
	v_rcp_f32_e32 v226, v226
	v_rcp_f32_e32 v227, v227
	v_pk_mul_f32 v[78:79], v[78:79], v[190:191]
	v_mfma_f32_16x16x32_bf16 v[34:37], v[176:179], v[204:207], v[34:37]
	v_pk_mul_f32 v[80:81], v[80:81], v[192:193]
	v_pk_mul_f32 v[70:71], v[70:71], v[224:225]
	v_pk_mul_f32 v[72:73], v[72:73], v[226:227]
	v_pk_mul_f32 v[78:79], v[78:79], v[74:75]
	v_pk_mul_f32 v[80:81], v[80:81], v[76:77]
	v_pk_mul_f32 v[70:71], v[70:71], v[66:67]
	v_mfma_f32_16x16x32_bf16 v[26:29], v[168:171], v[212:215], v[26:29]
	v_pk_mul_f32 v[72:73], v[72:73], v[68:69]
	v_cvt_pk_bf16_f32 v66, v78, v79
	v_cvt_pk_bf16_f32 v67, v80, v81
	v_cvt_pk_bf16_f32 v68, v70, v71
	v_cvt_pk_bf16_f32 v69, v72, v73
	global_store_dwordx4 v[86:87], v[66:69], off offset:2048
	v_mfma_f32_16x16x32_bf16 v[18:21], v[176:179], v[212:215], v[18:21]
	v_mfma_f32_16x16x32_bf16 v[10:13], v[168:171], v[220:223], v[10:13]
	v_mfma_f32_16x16x32_bf16 v[2:5], v[176:179], v[220:223], v[2:5]
	s_setprio 0
	s_barrier
	s_add_i32 s83, s83, 2
	s_add_u32 s26, s26, 0x10000
	s_addc_u32 s27, s27, 0
	s_add_u32 s73, s73, 0x10000
	s_addc_u32 s81, s81, 0
	s_branch .Lpost_1340
; __device__ __forceinline__ float fast_sigmoid(float x) { return __builtin_amdgcn_rcpf(1.0f + __builtin_amdgcn_exp2f(-1.4426950408889634f * x)); }
; __device__ __forceinline__ u32x4 pack8(const f32x4 v0, const f32x4 v1) { u32x4 w; w.x = cvt_pk_bf16(v0[0], v0[1]); w.y = cvt_pk_bf16(v0[2], v0[3]); w.z = cvt_pk_bf16(v1[0], v1[1]); w.w = cvt_pk_bf16(v1[2], v1[3]); return w; }
; #define PG8_BAR __builtin_amdgcn_s_barrier()
;     __device__ __forceinline__ void operator()(const f32x4 (&acc)[2][2][4][2], const Unit& u, int wr, int wc, int fr_, int fq) const {
;     ...
;         bf16_t* Hblk = H + ((size_t)(u.pm * (ldh / BK) + 2 * u.pn + (wc >> 1)) * BM + wr * 64 + fr) * BK + (wc & 1) * 32 + 8 * fq;
; #pragma unroll
;         for (int ai = 0; ai < 2; ++ai)
; #pragma unroll
;             for (int m = 0; m < 4; ++m) {
;                 f32x4 v0, v1;
; #pragma unroll
;                 for (int j = 0; j < 4; ++j) { const float g0 = acc[ai][0][m][0][j], g1 = acc[ai][0][m][1][j];
;                     v0[j] = g0 * fast_sigmoid(g0) * acc[ai][1][m][0][j]; v1[j] = g1 * fast_sigmoid(g1) * acc[ai][1][m][1][j]; }
;                 *(u32x4*)(Hblk + (size_t)(ai * HALF + m * 16) * BK) = pack8(v0, v1); }
; template <class Epi, class Sched, bool ALIGN_EPI = false, bool SP2 = false, bool ABLK = false, bool BBLK = false>
; __device__ __forceinline__ void gemm_phase(PG8_LAS unsigned char* lds, const Gemm g, const Sched& S, const Epi& E) {
;     ...
;         if constexpr (ALIGN_EPI) { if (wr == 0) PG8_BAR; }
;         if constexpr (!Epi::AFTER_DRAIN) { E(acc, cur, wr, wc, fr, fq); S.done(cur); }
;         if (!has_next) break;
; #pragma unroll
;         for (int a = 0; a < 2; ++a)
; #pragma unroll
;             for (int b = 0; b < 2; ++b)
; #pragma unroll
;                 for (int m = 0; m < 4; ++m)
; #pragma unroll
;                     for (int n = 0; n < 2; ++n) acc[a][b][m][n] = (f32x4){0.f, 0.f, 0.f, 0.f};
;         cur = nxt; cA = nA; cB = nB; ++ui;
;         if constexpr (ALIGN_EPI) { if (wr == 1) PG8_BAR; }
;     }
.Lpost_1340:
	s_and_b64 vcc, exec, s[12:13]
	s_cbranch_vccz .LBB0_1343
	s_barrier
.LBB0_1343:
	v_pk_mul_f32 v[190:191], v[62:63], v[184:185]
	v_pk_mul_f32 v[192:193], v[64:65], v[184:185]
	v_pk_mul_f32 v[224:225], v[54:55], v[184:185]
	v_pk_mul_f32 v[226:227], v[56:57], v[184:185]
	v_exp_f32_e32 v190, v190
	v_exp_f32_e32 v191, v191
	v_exp_f32_e32 v192, v192
	v_exp_f32_e32 v193, v193
	v_exp_f32_e32 v224, v224
	v_exp_f32_e32 v225, v225
	v_exp_f32_e32 v226, v226
	v_exp_f32_e32 v227, v227
	v_pk_add_f32 v[190:191], v[190:191], v[188:189]
	v_pk_add_f32 v[192:193], v[192:193], v[188:189]
	v_pk_add_f32 v[224:225], v[224:225], v[188:189]
	v_pk_add_f32 v[226:227], v[226:227], v[188:189]
	v_rcp_f32_e32 v190, v190
	v_rcp_f32_e32 v191, v191
	v_rcp_f32_e32 v192, v192
	v_rcp_f32_e32 v193, v193
	v_rcp_f32_e32 v224, v224
	v_rcp_f32_e32 v225, v225
	v_rcp_f32_e32 v226, v226
	v_rcp_f32_e32 v227, v227
	v_pk_mul_f32 v[62:63], v[62:63], v[190:191]
	v_pk_mul_f32 v[64:65], v[64:65], v[192:193]
	v_pk_mul_f32 v[54:55], v[54:55], v[224:225]
	v_pk_mul_f32 v[56:57], v[56:57], v[226:227]
	v_pk_mul_f32 v[62:63], v[62:63], v[58:59]
	v_pk_mul_f32 v[64:65], v[64:65], v[60:61]
	v_pk_mul_f32 v[54:55], v[54:55], v[50:51]
	v_pk_mul_f32 v[56:57], v[56:57], v[52:53]
	v_cvt_pk_bf16_f32 v52, v62, v63
	v_cvt_pk_bf16_f32 v53, v64, v65
	v_cvt_pk_bf16_f32 v54, v54, v55
	v_cvt_pk_bf16_f32 v55, v56, v57
	v_add_co_u32_e32 v56, vcc, s87, v142
	s_nop 1
	v_addc_co_u32_e32 v57, vcc, 0, v143, vcc
	v_add_co_u32_e32 v50, vcc, s0, v142
	s_nop 1
	s_mov_b64 s[0:1], -1
	v_addc_co_u32_e32 v51, vcc, 0, v143, vcc
	global_store_dwordx4 v[50:51], v[52:55], off offset:-4096
	v_pk_mul_f32 v[190:191], v[46:47], v[184:185]
	v_pk_mul_f32 v[192:193], v[48:49], v[184:185]
	v_pk_mul_f32 v[224:225], v[38:39], v[184:185]
	v_pk_mul_f32 v[226:227], v[40:41], v[184:185]
	v_exp_f32_e32 v190, v190
	v_exp_f32_e32 v191, v191
	v_exp_f32_e32 v192, v192
	v_exp_f32_e32 v193, v193
	v_exp_f32_e32 v224, v224
	v_exp_f32_e32 v225, v225
	v_exp_f32_e32 v226, v226
	v_exp_f32_e32 v227, v227
	v_pk_add_f32 v[190:191], v[190:191], v[188:189]
	v_pk_add_f32 v[192:193], v[192:193], v[188:189]
	v_pk_add_f32 v[224:225], v[224:225], v[188:189]
	v_pk_add_f32 v[226:227], v[226:227], v[188:189]
	v_rcp_f32_e32 v190, v190
	v_rcp_f32_e32 v191, v191
	v_rcp_f32_e32 v192, v192
	v_rcp_f32_e32 v193, v193
	v_rcp_f32_e32 v224, v224
	v_rcp_f32_e32 v225, v225
	v_rcp_f32_e32 v226, v226
	v_rcp_f32_e32 v227, v227
	v_pk_mul_f32 v[46:47], v[46:47], v[190:191]
	v_pk_mul_f32 v[48:49], v[48:49], v[192:193]
	v_pk_mul_f32 v[38:39], v[38:39], v[224:225]
	v_pk_mul_f32 v[40:41], v[40:41], v[226:227]
	v_pk_mul_f32 v[46:47], v[46:47], v[42:43]
	v_pk_mul_f32 v[48:49], v[48:49], v[44:45]
	v_pk_mul_f32 v[38:39], v[38:39], v[34:35]
	v_pk_mul_f32 v[40:41], v[40:41], v[36:37]
	v_cvt_pk_bf16_f32 v34, v46, v47
	v_cvt_pk_bf16_f32 v35, v48, v49
	v_cvt_pk_bf16_f32 v36, v38, v39
	v_cvt_pk_bf16_f32 v37, v40, v41
	s_andn2_b64 vcc, exec, s[6:7]
	global_store_dwordx4 v[56:57], v[34:37], off offset:2048
	v_pk_mul_f32 v[190:191], v[30:31], v[184:185]
	v_pk_mul_f32 v[192:193], v[32:33], v[184:185]
	v_pk_mul_f32 v[224:225], v[22:23], v[184:185]
	v_pk_mul_f32 v[226:227], v[24:25], v[184:185]
	v_exp_f32_e32 v190, v190
	v_exp_f32_e32 v191, v191
	v_exp_f32_e32 v192, v192
	v_exp_f32_e32 v193, v193
	v_exp_f32_e32 v224, v224
	v_exp_f32_e32 v225, v225
	v_exp_f32_e32 v226, v226
	v_exp_f32_e32 v227, v227
	v_pk_add_f32 v[190:191], v[190:191], v[188:189]
	v_pk_add_f32 v[192:193], v[192:193], v[188:189]
	v_pk_add_f32 v[224:225], v[224:225], v[188:189]
	v_pk_add_f32 v[226:227], v[226:227], v[188:189]
	v_rcp_f32_e32 v190, v190
	v_rcp_f32_e32 v191, v191
	v_rcp_f32_e32 v192, v192
	v_rcp_f32_e32 v193, v193
	v_rcp_f32_e32 v224, v224
	v_rcp_f32_e32 v225, v225
	v_rcp_f32_e32 v226, v226
	v_rcp_f32_e32 v227, v227
	v_pk_mul_f32 v[30:31], v[30:31], v[190:191]
	v_pk_mul_f32 v[32:33], v[32:33], v[192:193]
	v_pk_mul_f32 v[22:23], v[22:23], v[224:225]
	v_pk_mul_f32 v[24:25], v[24:25], v[226:227]
	v_pk_mul_f32 v[30:31], v[30:31], v[26:27]
	v_pk_mul_f32 v[32:33], v[32:33], v[28:29]
	v_pk_mul_f32 v[22:23], v[22:23], v[18:19]
	v_pk_mul_f32 v[24:25], v[24:25], v[20:21]
	v_cvt_pk_bf16_f32 v18, v30, v31
	v_cvt_pk_bf16_f32 v19, v32, v33
	v_cvt_pk_bf16_f32 v20, v22, v23
	v_cvt_pk_bf16_f32 v21, v24, v25
	global_store_dwordx4 v[50:51], v[18:21], off
	v_pk_mul_f32 v[190:191], v[14:15], v[184:185]
	v_pk_mul_f32 v[192:193], v[16:17], v[184:185]
	v_pk_mul_f32 v[224:225], v[6:7], v[184:185]
	v_pk_mul_f32 v[226:227], v[8:9], v[184:185]
	v_exp_f32_e32 v190, v190
	v_exp_f32_e32 v191, v191
	v_exp_f32_e32 v192, v192
	v_exp_f32_e32 v193, v193
	v_exp_f32_e32 v224, v224
	v_exp_f32_e32 v225, v225
	v_exp_f32_e32 v226, v226
	v_exp_f32_e32 v227, v227
	v_pk_add_f32 v[190:191], v[190:191], v[188:189]
	v_pk_add_f32 v[192:193], v[192:193], v[188:189]
	v_pk_add_f32 v[224:225], v[224:225], v[188:189]
	v_pk_add_f32 v[226:227], v[226:227], v[188:189]
	v_rcp_f32_e32 v190, v190
	v_rcp_f32_e32 v191, v191
	v_rcp_f32_e32 v192, v192
	v_rcp_f32_e32 v193, v193
	v_rcp_f32_e32 v224, v224
	v_rcp_f32_e32 v225, v225
	v_rcp_f32_e32 v226, v226
	v_rcp_f32_e32 v227, v227
	v_pk_mul_f32 v[14:15], v[14:15], v[190:191]
	v_pk_mul_f32 v[16:17], v[16:17], v[192:193]
	v_pk_mul_f32 v[6:7], v[6:7], v[224:225]
	v_pk_mul_f32 v[8:9], v[8:9], v[226:227]
	v_pk_mul_f32 v[14:15], v[14:15], v[10:11]
	v_pk_mul_f32 v[16:17], v[16:17], v[12:13]
	v_pk_mul_f32 v[6:7], v[6:7], v[2:3]
	v_pk_mul_f32 v[8:9], v[8:9], v[4:5]
	v_cvt_pk_bf16_f32 v2, v14, v15
	v_cvt_pk_bf16_f32 v3, v16, v17
	v_cvt_pk_bf16_f32 v4, v6, v7
	v_cvt_pk_bf16_f32 v5, v8, v9
	global_store_dwordx4 v[50:51], v[2:5], off offset:2048
	s_cbranch_vccnz .LBB0_1336
	s_andn2_b64 vcc, exec, s[4:5]
	s_cbranch_vccnz .LBB0_1335
	s_barrier
	s_branch .LBB0_1335
